# v40 plus the seven K-loop heads aligned to 64 bytes (code placement)
# speedup vs baseline: 1.0001x; 1.0001x over previous
;     __device__ __forceinline__ size_t aoff(const Unit& u) const { return (size_t)u.pm * bm * lda * 2; }
;     __device__ __forceinline__ size_t boff(const Unit& u) const { return (size_t)u.pn * BM * ldb * 2; }
;     __device__ __forceinline__ size_t aoff(const Unit& u) const { return ((size_t)u.pm * BM * lda + (size_t)u.pn * akoff) * 2; }
;     __device__ __forceinline__ size_t boff(const Unit& u) const { return (size_t)u.pn * BM * ldb * 2; }
;     __device__ __forceinline__ size_t aoff(const Unit& u) const { return ((size_t)u.pm * BM * lda + (size_t)(u.pn >> 1) * akoff) * 2; }
;     __device__ __forceinline__ size_t boff(const Unit& u) const { return (size_t)u.pn * BM * ldb * 2; }
;     ...
;         const bool has_next = S.next(ui + 1, nxt);
;         const char* nA = has_next ? (const char*)g.A + S.aoff(nxt) : cA; const char* nB = has_next ? (const char*)g.Bt + S.boff(nxt) : cB;
;         if constexpr (Epi::PRE) E.pre(lds, cur, wid);
;         for (int t = 0; t < nt; t += 2) {
;             const bool last = (t == nt - 2);
;             const char* a1 = cA + (size_t)(t + 1) * kstep;
;             const char* a2 = last ? nA : cA + (size_t)(t + 2) * kstep; const char* b2 = last ? nB : cB + (size_t)(t + 2) * kstep;
;             const char* a3 = a2 + kstep; const char* b3 = b2 + kstep;
;     ...
; #pragma unroll
;         for (int a = 0; a < 2; ++a)
; #pragma unroll
;             for (int b = 0; b < 2; ++b)
; #pragma unroll
;                 for (int m = 0; m < NM; ++m)
; #pragma unroll
;                     for (int n = 0; n < 2; ++n) acc[a][b][m][n] = (f32x4){0.f, 0.f, 0.f, 0.f};
;         cur = nxt; cA = nA; cB = nB; ++ui; cur.par = ui & 1;
.LBB0_199:
	s_ashr_i32 s23, s22, 31
	s_lshl_b64 s[2:3], s[22:23], 20
	s_add_u32 s24, s33, s2
	s_addc_u32 s25, s36, s3
	s_and_b64 s[2:3], s[4:5], exec
	s_cselect_b32 s2, s25, s29
	s_cselect_b32 s3, s24, s28
	s_ashr_i32 s21, s20, 31
	s_lshl_b64 s[26:27], s[20:21], 20
	s_add_u32 s26, s37, s26
	s_addc_u32 s27, s38, s27
	s_and_b64 s[34:35], s[4:5], exec
	s_cselect_b32 s9, s27, s31
	s_cselect_b32 s21, s26, s30
	s_add_u32 s28, s28, 0x80080
	s_addc_u32 s29, s29, 0
	s_add_u32 s23, s30, 0x100
	v_mov_b32_e32 v2, 0
	s_addc_u32 s54, s31, 0
	s_mov_b32 s56, -2
	v_mov_b32_e32 v3, v2
	v_mov_b32_e32 v4, v2
	v_mov_b32_e32 v5, v2
	v_mov_b32_e32 v6, v2
	v_mov_b32_e32 v7, v2
	v_mov_b32_e32 v8, v2
	v_mov_b32_e32 v9, v2
	v_mov_b32_e32 v18, v2
	v_mov_b32_e32 v19, v2
	v_mov_b32_e32 v20, v2
	v_mov_b32_e32 v21, v2
	v_mov_b32_e32 v22, v2
	v_mov_b32_e32 v23, v2
	v_mov_b32_e32 v24, v2
	v_mov_b32_e32 v25, v2
	v_mov_b32_e32 v50, v2
	v_mov_b32_e32 v51, v2
	v_mov_b32_e32 v52, v2
	v_mov_b32_e32 v53, v2
	v_mov_b32_e32 v54, v2
	v_mov_b32_e32 v55, v2
	v_mov_b32_e32 v56, v2
	v_mov_b32_e32 v57, v2
	v_mov_b32_e32 v66, v2
	s_waitcnt vmcnt(0)
	v_mov_b32_e32 v67, v2
	v_mov_b32_e32 v68, v2
	v_mov_b32_e32 v69, v2
	v_mov_b32_e32 v70, v2
	v_mov_b32_e32 v71, v2
	v_mov_b32_e32 v72, v2
	v_mov_b32_e32 v73, v2
	v_mov_b32_e32 v10, v2
	v_mov_b32_e32 v11, v2
	v_mov_b32_e32 v12, v2
	v_mov_b32_e32 v13, v2
	v_mov_b32_e32 v14, v2
	v_mov_b32_e32 v15, v2
	v_mov_b32_e32 v16, v2
	v_mov_b32_e32 v17, v2
	v_mov_b32_e32 v34, v2
	v_mov_b32_e32 v35, v2
	v_mov_b32_e32 v36, v2
	v_mov_b32_e32 v37, v2
	v_mov_b32_e32 v38, v2
	v_mov_b32_e32 v39, v2
	v_mov_b32_e32 v40, v2
	v_mov_b32_e32 v41, v2
	v_mov_b32_e32 v58, v2
	v_mov_b32_e32 v59, v2
	v_mov_b32_e32 v60, v2
	v_mov_b32_e32 v61, v2
	v_mov_b32_e32 v62, v2
	v_mov_b32_e32 v63, v2
	v_mov_b32_e32 v64, v2
	v_mov_b32_e32 v65, v2
	v_mov_b32_e32 v74, v2
	v_mov_b32_e32 v75, v2
	v_mov_b32_e32 v76, v2
	v_mov_b32_e32 v77, v2
	v_mov_b32_e32 v78, v2
	v_mov_b32_e32 v79, v2
	v_mov_b32_e32 v80, v2
	v_mov_b32_e32 v81, v2
	v_mov_b32_e32 v82, v2
	v_mov_b32_e32 v83, v2
	v_mov_b32_e32 v84, v2
	v_mov_b32_e32 v85, v2
	v_mov_b32_e32 v86, v2
	v_mov_b32_e32 v87, v2
	v_mov_b32_e32 v88, v2
	v_mov_b32_e32 v89, v2
	v_mov_b32_e32 v98, v2
	v_mov_b32_e32 v99, v2
	v_mov_b32_e32 v100, v2
	v_mov_b32_e32 v101, v2
	v_mov_b32_e32 v102, v2
	v_mov_b32_e32 v103, v2
	v_mov_b32_e32 v104, v2
	v_mov_b32_e32 v105, v2
	v_mov_b32_e32 v114, v2
	v_mov_b32_e32 v115, v2
	v_mov_b32_e32 v116, v2
	v_mov_b32_e32 v117, v2
	v_mov_b32_e32 v118, v2
	v_mov_b32_e32 v119, v2
	v_mov_b32_e32 v120, v2
	v_mov_b32_e32 v121, v2
	v_mov_b32_e32 v130, v2
	v_mov_b32_e32 v131, v2
	v_mov_b32_e32 v132, v2
	v_mov_b32_e32 v133, v2
	v_mov_b32_e32 v134, v2
	v_mov_b32_e32 v135, v2
	v_mov_b32_e32 v136, v2
	v_mov_b32_e32 v137, v2
	v_mov_b32_e32 v90, v2
	v_mov_b32_e32 v91, v2
	v_mov_b32_e32 v92, v2
	v_mov_b32_e32 v93, v2
	v_mov_b32_e32 v94, v2
	v_mov_b32_e32 v95, v2
	v_mov_b32_e32 v96, v2
	v_mov_b32_e32 v97, v2
	v_mov_b32_e32 v106, v2
	v_mov_b32_e32 v107, v2
	v_mov_b32_e32 v108, v2
	v_mov_b32_e32 v109, v2
	v_mov_b32_e32 v110, v2
	v_mov_b32_e32 v111, v2
	v_mov_b32_e32 v112, v2
	v_mov_b32_e32 v113, v2
	v_mov_b32_e32 v122, v2
	v_mov_b32_e32 v123, v2
	v_mov_b32_e32 v124, v2
	v_mov_b32_e32 v125, v2
	v_mov_b32_e32 v126, v2
	v_mov_b32_e32 v127, v2
	v_mov_b32_e32 v128, v2
	v_mov_b32_e32 v129, v2
	v_mov_b32_e32 v138, v2
	v_mov_b32_e32 v139, v2
	v_mov_b32_e32 v140, v2
	v_mov_b32_e32 v141, v2
	v_mov_b32_e32 v142, v2
	v_mov_b32_e32 v143, v2
	v_mov_b32_e32 v144, v2
	v_mov_b32_e32 v145, v2
	.p2align 6

;     __device__ __forceinline__ size_t aoff(const Unit& u) const { return (size_t)u.pm * bm * lda * 2; }
;     __device__ __forceinline__ size_t boff(const Unit& u) const { return (size_t)u.pn * BM * ldb * 2; }
;     __device__ __forceinline__ size_t aoff(const Unit& u) const { return ((size_t)u.pm * BM * lda + (size_t)u.pn * akoff) * 2; }
;     __device__ __forceinline__ size_t boff(const Unit& u) const { return (size_t)u.pn * BM * ldb * 2; }
;     __device__ __forceinline__ size_t aoff(const Unit& u) const { return ((size_t)u.pm * BM * lda + (size_t)(u.pn >> 1) * akoff) * 2; }
;     __device__ __forceinline__ size_t boff(const Unit& u) const { return (size_t)u.pn * BM * ldb * 2; }
;     ...
;         const bool has_next = S.next(ui + 1, nxt);
;         const char* nA = has_next ? (const char*)g.A + S.aoff(nxt) : cA; const char* nB = has_next ? (const char*)g.Bt + S.boff(nxt) : cB;
;         if constexpr (Epi::PRE) E.pre(lds, cur, wid);
;         for (int t = 0; t < nt; t += 2) {
;             const bool last = (t == nt - 2);
;             const char* a1 = cA + (size_t)(t + 1) * kstep;
;             const char* a2 = last ? nA : cA + (size_t)(t + 2) * kstep; const char* b2 = last ? nB : cB + (size_t)(t + 2) * kstep;
;             const char* a3 = a2 + kstep; const char* b3 = b2 + kstep;
;     ...
; #pragma unroll
;         for (int a = 0; a < 2; ++a)
; #pragma unroll
;             for (int b = 0; b < 2; ++b)
; #pragma unroll
;                 for (int m = 0; m < NM; ++m)
; #pragma unroll
;                     for (int n = 0; n < 2; ++n) acc[a][b][m][n] = (f32x4){0.f, 0.f, 0.f, 0.f};
;         cur = nxt; cA = nA; cB = nB; ++ui; cur.par = ui & 1;
.LBB0_702:
	s_ashr_i32 s29, s28, 31
	s_lshl_b64 s[2:3], s[28:29], 20
	s_add_u32 s30, s33, s2
	s_addc_u32 s31, s47, s3
	s_and_b64 s[2:3], s[4:5], exec
	s_cselect_b32 s2, s31, s11
	s_cselect_b32 s3, s30, s10
	s_ashr_i32 s27, s26, 31
	s_lshl_b64 s[34:35], s[26:27], 20
	s_add_u32 s34, s48, s34
	s_addc_u32 s35, s49, s35
	s_and_b64 s[36:37], s[4:5], exec
	s_cselect_b32 s9, s35, s13
	s_cselect_b32 s27, s34, s12
	s_add_u32 s10, s10, 0x80080
	s_addc_u32 s11, s11, 0
	s_add_u32 s29, s12, 0x100
	v_mov_b32_e32 v2, 0
	s_addc_u32 s38, s13, 0
	s_mov_b32 s39, -2
	v_mov_b32_e32 v3, v2
	v_mov_b32_e32 v4, v2
	v_mov_b32_e32 v5, v2
	v_mov_b32_e32 v6, v2
	v_mov_b32_e32 v7, v2
	v_mov_b32_e32 v8, v2
	v_mov_b32_e32 v9, v2
	v_mov_b32_e32 v18, v2
	v_mov_b32_e32 v19, v2
	v_mov_b32_e32 v20, v2
	v_mov_b32_e32 v21, v2
	v_mov_b32_e32 v22, v2
	v_mov_b32_e32 v23, v2
	v_mov_b32_e32 v24, v2
	v_mov_b32_e32 v25, v2
	v_mov_b32_e32 v34, v2
	v_mov_b32_e32 v35, v2
	v_mov_b32_e32 v36, v2
	v_mov_b32_e32 v37, v2
	v_mov_b32_e32 v38, v2
	v_mov_b32_e32 v39, v2
	v_mov_b32_e32 v40, v2
	v_mov_b32_e32 v41, v2
	v_mov_b32_e32 v50, v2
	v_mov_b32_e32 v51, v2
	v_mov_b32_e32 v52, v2
	v_mov_b32_e32 v53, v2
	v_mov_b32_e32 v54, v2
	v_mov_b32_e32 v55, v2
	v_mov_b32_e32 v56, v2
	v_mov_b32_e32 v57, v2
	v_mov_b32_e32 v10, v2
	v_mov_b32_e32 v11, v2
	v_mov_b32_e32 v12, v2
	v_mov_b32_e32 v13, v2
	v_mov_b32_e32 v14, v2
	v_mov_b32_e32 v15, v2
	v_mov_b32_e32 v16, v2
	v_mov_b32_e32 v17, v2
	v_mov_b32_e32 v26, v2
	v_mov_b32_e32 v27, v2
	v_mov_b32_e32 v28, v2
	v_mov_b32_e32 v29, v2
	v_mov_b32_e32 v30, v2
	v_mov_b32_e32 v31, v2
	v_mov_b32_e32 v32, v2
	v_mov_b32_e32 v33, v2
	v_mov_b32_e32 v42, v2
	v_mov_b32_e32 v43, v2
	v_mov_b32_e32 v44, v2
	v_mov_b32_e32 v45, v2
	v_mov_b32_e32 v46, v2
	v_mov_b32_e32 v47, v2
	v_mov_b32_e32 v48, v2
	v_mov_b32_e32 v49, v2
	v_mov_b32_e32 v58, v2
	v_mov_b32_e32 v59, v2
	v_mov_b32_e32 v60, v2
	v_mov_b32_e32 v61, v2
	v_mov_b32_e32 v62, v2
	v_mov_b32_e32 v63, v2
	v_mov_b32_e32 v64, v2
	v_mov_b32_e32 v65, v2
	v_mov_b32_e32 v66, v2
	v_mov_b32_e32 v67, v2
	v_mov_b32_e32 v68, v2
	v_mov_b32_e32 v69, v2
	v_mov_b32_e32 v70, v2
	v_mov_b32_e32 v71, v2
	v_mov_b32_e32 v72, v2
	v_mov_b32_e32 v73, v2
	v_mov_b32_e32 v82, v2
	v_mov_b32_e32 v83, v2
	v_mov_b32_e32 v84, v2
	v_mov_b32_e32 v85, v2
	v_mov_b32_e32 v86, v2
	v_mov_b32_e32 v87, v2
	v_mov_b32_e32 v88, v2
	v_mov_b32_e32 v89, v2
	v_mov_b32_e32 v98, v2
	v_mov_b32_e32 v99, v2
	v_mov_b32_e32 v100, v2
	v_mov_b32_e32 v101, v2
	v_mov_b32_e32 v102, v2
	v_mov_b32_e32 v103, v2
	v_mov_b32_e32 v104, v2
	v_mov_b32_e32 v105, v2
	v_mov_b32_e32 v114, v2
	v_mov_b32_e32 v115, v2
	v_mov_b32_e32 v116, v2
	v_mov_b32_e32 v117, v2
	v_mov_b32_e32 v118, v2
	v_mov_b32_e32 v119, v2
	v_mov_b32_e32 v120, v2
	v_mov_b32_e32 v121, v2
	v_mov_b32_e32 v74, v2
	v_mov_b32_e32 v75, v2
	v_mov_b32_e32 v76, v2
	v_mov_b32_e32 v77, v2
	v_mov_b32_e32 v78, v2
	v_mov_b32_e32 v79, v2
	v_mov_b32_e32 v80, v2
	v_mov_b32_e32 v81, v2
	v_mov_b32_e32 v90, v2
	v_mov_b32_e32 v91, v2
	v_mov_b32_e32 v92, v2
	v_mov_b32_e32 v93, v2
	v_mov_b32_e32 v94, v2
	v_mov_b32_e32 v95, v2
	v_mov_b32_e32 v96, v2
	v_mov_b32_e32 v97, v2
	v_mov_b32_e32 v106, v2
	v_mov_b32_e32 v107, v2
	v_mov_b32_e32 v108, v2
	v_mov_b32_e32 v109, v2
	v_mov_b32_e32 v110, v2
	v_mov_b32_e32 v111, v2
	v_mov_b32_e32 v112, v2
	v_mov_b32_e32 v113, v2
	v_mov_b32_e32 v122, v2
	v_mov_b32_e32 v123, v2
	v_mov_b32_e32 v124, v2
	v_mov_b32_e32 v125, v2
	v_mov_b32_e32 v126, v2
	v_mov_b32_e32 v127, v2
	v_mov_b32_e32 v128, v2
	v_mov_b32_e32 v129, v2
	.p2align 6

; #define LAS __attribute__((address_space(3)))
; __device__ __forceinline__ int lane_id() { int l; asm volatile("v_mbcnt_lo_u32_b32 %0, -1, 0\n\tv_mbcnt_hi_u32_b32 %0, -1, %0" : "=v"(l)); return l; }
;     __device__ __forceinline__ size_t aoff(const Unit& u) const { return (size_t)u.pm * bm * lda * 2; }
;     __device__ __forceinline__ size_t boff(const Unit& u) const { return (size_t)u.pn * BM * ldb * 2; }
;     __device__ __forceinline__ size_t aoff(const Unit& u) const { return ((size_t)u.pm * BM * lda + (size_t)u.pn * akoff) * 2; }
;     __device__ __forceinline__ size_t boff(const Unit& u) const { return (size_t)u.pn * BM * ldb * 2; }
;     __device__ __forceinline__ size_t aoff(const Unit& u) const { return ((size_t)u.pm * BM * lda + (size_t)(u.pn >> 1) * akoff) * 2; }
;     __device__ __forceinline__ size_t boff(const Unit& u) const { return (size_t)u.pn * BM * ldb * 2; }
;     ...
;         const bool has_next = S.next(ui + 1, nxt);
;         const char* nA = has_next ? (const char*)g.A + S.aoff(nxt) : cA; const char* nB = has_next ? (const char*)g.Bt + S.boff(nxt) : cB;
;         if constexpr (Epi::PRE) E.pre(lds, cur, wid);
;         for (int t = 0; t < nt; t += 2) {
;             const bool last = (t == nt - 2);
;             const char* a1 = cA + (size_t)(t + 1) * kstep;
;             const char* a2 = last ? nA : cA + (size_t)(t + 2) * kstep; const char* b2 = last ? nB : cB + (size_t)(t + 2) * kstep;
;             const char* a3 = a2 + kstep; const char* b3 = b2 + kstep;
;     __device__ __forceinline__ void pre(LAS unsigned char* l, const pg8::Unit& u, int wid) const {
;         const float* src = (const float*)(ws + WS_SSQQ) + ((size_t)li * 8 + wid) * MT + u.pm * 256 + lane_id() * 4;
;         __builtin_amdgcn_global_load_lds((const unsigned*)src, (LAS unsigned*)(l + EPI_LDS + u.par * 8192 + wid * 1024), 16, 0, 0);
;     }
.LBB0_1191:
	s_ashr_i32 s27, s26, 31
	s_lshl_b64 s[2:3], s[26:27], 18
	s_add_u32 s28, s33, s2
	s_addc_u32 s29, s43, s3
	s_and_b64 s[2:3], s[4:5], exec
	s_cselect_b32 s2, s29, s11
	s_cselect_b32 s3, s28, s10
	s_ashr_i32 s25, s24, 31
	s_lshl_b64 s[30:31], s[24:25], 18
	s_add_u32 s30, s44, s30
	s_addc_u32 s31, s45, s31
	s_and_b64 s[56:57], s[4:5], exec
	s_cselect_b32 s7, s31, s13
	s_cselect_b32 s27, s30, s12
	s_lshl_b32 s8, s8, 8
	s_ashr_i32 s9, s8, 31
	s_lshl_b64 s[56:57], s[8:9], 2
	s_add_u32 s56, s94, s56
	v_mbcnt_lo_u32_b32 v0, -1, 0
	v_mbcnt_hi_u32_b32 v0, -1, v0
	s_addc_u32 s57, s95, s57
	v_lshlrev_b32_e32 v2, 2, v0
	v_ashrrev_i32_e32 v3, 31, v2
	s_lshl_b32 s25, s34, 13
	v_lshl_add_u64 v[2:3], v[2:3], 2, s[56:57]
	s_add_i32 m0, s81, s25
	s_add_u32 s10, s10, 0x20080
	global_load_lds_dwordx4 v[2:3], off
	s_addc_u32 s11, s11, 0
	s_add_u32 s9, s12, 0x100
	v_mov_b32_e32 v66, 0
	s_addc_u32 s52, s13, 0
	s_mov_b32 s54, -2
	v_mov_b32_e32 v67, v66
	v_mov_b32_e32 v68, v66
	v_mov_b32_e32 v69, v66
	v_mov_b32_e32 v70, v66
	v_mov_b32_e32 v71, v66
	v_mov_b32_e32 v72, v66
	v_mov_b32_e32 v73, v66
	v_mov_b32_e32 v82, v66
	v_mov_b32_e32 v83, v66
	v_mov_b32_e32 v84, v66
	v_mov_b32_e32 v85, v66
	v_mov_b32_e32 v86, v66
	v_mov_b32_e32 v87, v66
	v_mov_b32_e32 v88, v66
	v_mov_b32_e32 v89, v66
	v_mov_b32_e32 v98, v66
	v_mov_b32_e32 v99, v66
	v_mov_b32_e32 v100, v66
	v_mov_b32_e32 v101, v66
	v_mov_b32_e32 v102, v66
	v_mov_b32_e32 v103, v66
	v_mov_b32_e32 v104, v66
	v_mov_b32_e32 v105, v66
	v_mov_b32_e32 v114, v66
	v_mov_b32_e32 v115, v66
	v_mov_b32_e32 v116, v66
	v_mov_b32_e32 v117, v66
	v_mov_b32_e32 v118, v66
	v_mov_b32_e32 v119, v66
	v_mov_b32_e32 v120, v66
	v_mov_b32_e32 v121, v66
	v_mov_b32_e32 v74, v66
	v_mov_b32_e32 v75, v66
	v_mov_b32_e32 v76, v66
	v_mov_b32_e32 v77, v66
	v_mov_b32_e32 v78, v66
	v_mov_b32_e32 v79, v66
	v_mov_b32_e32 v80, v66
	v_mov_b32_e32 v81, v66
	v_mov_b32_e32 v90, v66
	v_mov_b32_e32 v91, v66
	v_mov_b32_e32 v92, v66
	v_mov_b32_e32 v93, v66
	v_mov_b32_e32 v94, v66
	v_mov_b32_e32 v95, v66
	v_mov_b32_e32 v96, v66
	v_mov_b32_e32 v97, v66
	v_mov_b32_e32 v106, v66
	v_mov_b32_e32 v107, v66
	v_mov_b32_e32 v108, v66
	v_mov_b32_e32 v109, v66
	v_mov_b32_e32 v110, v66
	v_mov_b32_e32 v111, v66
	v_mov_b32_e32 v112, v66
	v_mov_b32_e32 v113, v66
	v_mov_b32_e32 v122, v66
	v_mov_b32_e32 v123, v66
	v_mov_b32_e32 v124, v66
	v_mov_b32_e32 v125, v66
	v_mov_b32_e32 v126, v66
	v_mov_b32_e32 v127, v66
	v_mov_b32_e32 v128, v66
	v_mov_b32_e32 v129, v66
	v_mov_b32_e32 v130, v66
	v_mov_b32_e32 v131, v66
	v_mov_b32_e32 v132, v66
	v_mov_b32_e32 v133, v66
	v_mov_b32_e32 v134, v66
	v_mov_b32_e32 v135, v66
	v_mov_b32_e32 v136, v66
	v_mov_b32_e32 v137, v66
	v_mov_b32_e32 v146, v66
	v_mov_b32_e32 v147, v66
	v_mov_b32_e32 v148, v66
	v_mov_b32_e32 v149, v66
	v_mov_b32_e32 v150, v66
	v_mov_b32_e32 v151, v66
	v_mov_b32_e32 v152, v66
	v_mov_b32_e32 v153, v66
	v_mov_b32_e32 v162, v66
	v_mov_b32_e32 v163, v66
	v_mov_b32_e32 v164, v66
	v_mov_b32_e32 v165, v66
	v_mov_b32_e32 v166, v66
	v_mov_b32_e32 v167, v66
	v_mov_b32_e32 v168, v66
	v_mov_b32_e32 v169, v66
	v_mov_b32_e32 v2, v66
	v_mov_b32_e32 v3, v66
	v_mov_b32_e32 v4, v66
	v_mov_b32_e32 v5, v66
	v_mov_b32_e32 v6, v66
	v_mov_b32_e32 v7, v66
	v_mov_b32_e32 v8, v66
	v_mov_b32_e32 v9, v66
	v_mov_b32_e32 v138, v66
	v_mov_b32_e32 v139, v66
	v_mov_b32_e32 v140, v66
	v_mov_b32_e32 v141, v66
	v_mov_b32_e32 v142, v66
	v_mov_b32_e32 v143, v66
	v_mov_b32_e32 v144, v66
	v_mov_b32_e32 v145, v66
	v_mov_b32_e32 v154, v66
	v_mov_b32_e32 v155, v66
	v_mov_b32_e32 v156, v66
	v_mov_b32_e32 v157, v66
	v_mov_b32_e32 v158, v66
	v_mov_b32_e32 v159, v66
	v_mov_b32_e32 v160, v66
	v_mov_b32_e32 v161, v66
	v_mov_b32_e32 v170, v66
	v_mov_b32_e32 v171, v66
	v_mov_b32_e32 v172, v66
	v_mov_b32_e32 v173, v66
	v_mov_b32_e32 v174, v66
	v_mov_b32_e32 v175, v66
	v_mov_b32_e32 v176, v66
	v_mov_b32_e32 v177, v66
	v_mov_b32_e32 v34, v66
	v_mov_b32_e32 v35, v66
	v_mov_b32_e32 v36, v66
	v_mov_b32_e32 v37, v66
	v_mov_b32_e32 v38, v66
	v_mov_b32_e32 v39, v66
	v_mov_b32_e32 v40, v66
	v_mov_b32_e32 v41, v66
	.p2align 6

;     __device__ __forceinline__ size_t aoff(const Unit& u) const { return (size_t)u.pm * bm * lda * 2; }
;     __device__ __forceinline__ size_t boff(const Unit& u) const { return (size_t)u.pn * BM * ldb * 2; }
;     __device__ __forceinline__ size_t aoff(const Unit& u) const { return ((size_t)u.pm * BM * lda + (size_t)u.pn * akoff) * 2; }
;     __device__ __forceinline__ size_t boff(const Unit& u) const { return (size_t)u.pn * BM * ldb * 2; }
;     __device__ __forceinline__ size_t aoff(const Unit& u) const { return ((size_t)u.pm * BM * lda + (size_t)(u.pn >> 1) * akoff) * 2; }
;     __device__ __forceinline__ size_t boff(const Unit& u) const { return (size_t)u.pn * BM * ldb * 2; }
;     ...
;         const bool has_next = S.next(ui + 1, nxt);
;         const char* nA = has_next ? (const char*)g.A + S.aoff(nxt) : cA; const char* nB = has_next ? (const char*)g.Bt + S.boff(nxt) : cB;
;         if constexpr (Epi::PRE) E.pre(lds, cur, wid);
;         for (int t = 0; t < nt; t += 2) {
;             const bool last = (t == nt - 2);
;             const char* a1 = cA + (size_t)(t + 1) * kstep;
;             const char* a2 = last ? nA : cA + (size_t)(t + 2) * kstep; const char* b2 = last ? nB : cB + (size_t)(t + 2) * kstep;
;             const char* a3 = a2 + kstep; const char* b3 = b2 + kstep;
;     ...
; #pragma unroll
;         for (int a = 0; a < 2; ++a)
; #pragma unroll
;             for (int b = 0; b < 2; ++b)
; #pragma unroll
;                 for (int m = 0; m < NM; ++m)
; #pragma unroll
;                     for (int n = 0; n < 2; ++n) acc[a][b][m][n] = (f32x4){0.f, 0.f, 0.f, 0.f};
;         cur = nxt; cA = nA; cB = nB; ++ui; cur.par = ui & 1;
.LBB0_1453:
	s_ashr_i32 s15, s14, 31
	s_lshl_b64 s[2:3], s[14:15], 18
	s_add_u32 s18, s29, s2
	s_addc_u32 s19, s30, s3
	s_and_b64 s[2:3], s[6:7], exec
	s_cselect_b32 s2, s19, s23
	s_cselect_b32 s3, s18, s22
	s_add_u32 s15, s22, 0x100
	v_mov_b32_e32 v2, 0
	s_addc_u32 s60, s23, 0
	s_mov_b32 s73, -2
	v_mov_b32_e32 v3, v2
	v_mov_b32_e32 v4, v2
	v_mov_b32_e32 v5, v2
	v_mov_b32_e32 v6, v2
	v_mov_b32_e32 v7, v2
	v_mov_b32_e32 v8, v2
	v_mov_b32_e32 v9, v2
	v_mov_b32_e32 v10, v2
	v_mov_b32_e32 v11, v2
	v_mov_b32_e32 v12, v2
	v_mov_b32_e32 v13, v2
	v_mov_b32_e32 v14, v2
	v_mov_b32_e32 v15, v2
	v_mov_b32_e32 v16, v2
	v_mov_b32_e32 v17, v2
	v_mov_b32_e32 v18, v2
	v_mov_b32_e32 v19, v2
	v_mov_b32_e32 v20, v2
	v_mov_b32_e32 v21, v2
	v_mov_b32_e32 v22, v2
	v_mov_b32_e32 v23, v2
	v_mov_b32_e32 v24, v2
	v_mov_b32_e32 v25, v2
	v_mov_b32_e32 v26, v2
	v_mov_b32_e32 v27, v2
	v_mov_b32_e32 v28, v2
	v_mov_b32_e32 v29, v2
	v_mov_b32_e32 v30, v2
	v_mov_b32_e32 v31, v2
	v_mov_b32_e32 v32, v2
	v_mov_b32_e32 v33, v2
	v_mov_b32_e32 v66, v2
	v_mov_b32_e32 v67, v2
	v_mov_b32_e32 v68, v2
	v_mov_b32_e32 v69, v2
	v_mov_b32_e32 v70, v2
	v_mov_b32_e32 v71, v2
	v_mov_b32_e32 v72, v2
	v_mov_b32_e32 v73, v2
	v_mov_b32_e32 v74, v2
	v_mov_b32_e32 v75, v2
	v_mov_b32_e32 v76, v2
	v_mov_b32_e32 v77, v2
	v_mov_b32_e32 v78, v2
	v_mov_b32_e32 v79, v2
	v_mov_b32_e32 v80, v2
	v_mov_b32_e32 v81, v2
	v_mov_b32_e32 v82, v2
	v_mov_b32_e32 v83, v2
	v_mov_b32_e32 v84, v2
	v_mov_b32_e32 v85, v2
	v_mov_b32_e32 v86, v2
	v_mov_b32_e32 v87, v2
	v_mov_b32_e32 v88, v2
	v_mov_b32_e32 v89, v2
	v_mov_b32_e32 v90, v2
	v_mov_b32_e32 v91, v2
	v_mov_b32_e32 v92, v2
	v_mov_b32_e32 v93, v2
	v_mov_b32_e32 v94, v2
	v_mov_b32_e32 v95, v2
	v_mov_b32_e32 v96, v2
	v_mov_b32_e32 v97, v2
	v_mov_b32_e32 v34, v2
	v_mov_b32_e32 v35, v2
	v_mov_b32_e32 v36, v2
	v_mov_b32_e32 v37, v2
	v_mov_b32_e32 v38, v2
	v_mov_b32_e32 v39, v2
	v_mov_b32_e32 v40, v2
	v_mov_b32_e32 v41, v2
	v_mov_b32_e32 v42, v2
	v_mov_b32_e32 v43, v2
	v_mov_b32_e32 v44, v2
	v_mov_b32_e32 v45, v2
	v_mov_b32_e32 v46, v2
	v_mov_b32_e32 v47, v2
	v_mov_b32_e32 v48, v2
	v_mov_b32_e32 v49, v2
	v_mov_b32_e32 v50, v2
	v_mov_b32_e32 v51, v2
	v_mov_b32_e32 v52, v2
	v_mov_b32_e32 v53, v2
	v_mov_b32_e32 v54, v2
	v_mov_b32_e32 v55, v2
	v_mov_b32_e32 v56, v2
	v_mov_b32_e32 v57, v2
	v_mov_b32_e32 v58, v2
	v_mov_b32_e32 v59, v2
	v_mov_b32_e32 v60, v2
	v_mov_b32_e32 v61, v2
	v_mov_b32_e32 v62, v2
	v_mov_b32_e32 v63, v2
	v_mov_b32_e32 v64, v2
	v_mov_b32_e32 v65, v2
	v_mov_b32_e32 v98, v2
	v_mov_b32_e32 v99, v2
	v_mov_b32_e32 v100, v2
	v_mov_b32_e32 v101, v2
	v_mov_b32_e32 v102, v2
	v_mov_b32_e32 v103, v2
	v_mov_b32_e32 v104, v2
	v_mov_b32_e32 v105, v2
	v_mov_b32_e32 v106, v2
	v_mov_b32_e32 v107, v2
	v_mov_b32_e32 v108, v2
	v_mov_b32_e32 v109, v2
	v_mov_b32_e32 v110, v2
	v_mov_b32_e32 v111, v2
	v_mov_b32_e32 v112, v2
	v_mov_b32_e32 v113, v2
	v_mov_b32_e32 v114, v2
	v_mov_b32_e32 v115, v2
	v_mov_b32_e32 v116, v2
	v_mov_b32_e32 v117, v2
	v_mov_b32_e32 v118, v2
	v_mov_b32_e32 v119, v2
	v_mov_b32_e32 v120, v2
	v_mov_b32_e32 v121, v2
	v_mov_b32_e32 v122, v2
	v_mov_b32_e32 v123, v2
	v_mov_b32_e32 v124, v2
	v_mov_b32_e32 v125, v2
	v_mov_b32_e32 v126, v2
	v_mov_b32_e32 v127, v2
	v_mov_b32_e32 v128, v2
	v_mov_b32_e32 v129, v2
	.p2align 6

;     __device__ __forceinline__ size_t aoff(const Unit& u) const { return (size_t)u.pm * bm * lda * 2; }
;     __device__ __forceinline__ size_t boff(const Unit& u) const { return (size_t)u.pn * BM * ldb * 2; }
;     __device__ __forceinline__ size_t aoff(const Unit& u) const { return ((size_t)u.pm * BM * lda + (size_t)u.pn * akoff) * 2; }
;     __device__ __forceinline__ size_t boff(const Unit& u) const { return (size_t)u.pn * BM * ldb * 2; }
;     __device__ __forceinline__ size_t aoff(const Unit& u) const { return ((size_t)u.pm * BM * lda + (size_t)(u.pn >> 1) * akoff) * 2; }
;     __device__ __forceinline__ size_t boff(const Unit& u) const { return (size_t)u.pn * BM * ldb * 2; }
;     ...
;         const bool has_next = S.next(ui + 1, nxt);
;         const char* nA = has_next ? (const char*)g.A + S.aoff(nxt) : cA; const char* nB = has_next ? (const char*)g.Bt + S.boff(nxt) : cB;
;         if constexpr (Epi::PRE) E.pre(lds, cur, wid);
;         for (int t = 0; t < nt; t += 2) {
;             const bool last = (t == nt - 2);
;             const char* a1 = cA + (size_t)(t + 1) * kstep;
;             const char* a2 = last ? nA : cA + (size_t)(t + 2) * kstep; const char* b2 = last ? nB : cB + (size_t)(t + 2) * kstep;
;             const char* a3 = a2 + kstep; const char* b3 = b2 + kstep;
;     ...
; #pragma unroll
;         for (int a = 0; a < 2; ++a)
; #pragma unroll
;             for (int b = 0; b < 2; ++b)
; #pragma unroll
;                 for (int m = 0; m < NM; ++m)
; #pragma unroll
;                     for (int n = 0; n < 2; ++n) acc[a][b][m][n] = (f32x4){0.f, 0.f, 0.f, 0.f};
;         cur = nxt; cA = nA; cB = nB; ++ui; cur.par = ui & 1;
.LBB0_1649:
	s_ashr_i32 s15, s14, 31
	s_lshl_b64 s[2:3], s[14:15], 20
	s_add_u32 s18, s5, s2
	s_addc_u32 s19, s26, s3
	s_and_b64 s[2:3], s[8:9], exec
	s_cselect_b32 s2, s19, s23
	s_cselect_b32 s3, s18, s22
	s_add_u32 s8, s24, 0x60080
	s_addc_u32 s9, s25, 0
	s_add_u32 s15, s22, 0x100
	v_mov_b32_e32 v2, 0
	s_addc_u32 s58, s23, 0
	s_mov_b32 s59, -2
	v_mov_b32_e32 v3, v2
	v_mov_b32_e32 v4, v2
	v_mov_b32_e32 v5, v2
	v_mov_b32_e32 v6, v2
	v_mov_b32_e32 v7, v2
	v_mov_b32_e32 v8, v2
	v_mov_b32_e32 v9, v2
	v_mov_b32_e32 v18, v2
	v_mov_b32_e32 v19, v2
	v_mov_b32_e32 v20, v2
	v_mov_b32_e32 v21, v2
	v_mov_b32_e32 v22, v2
	v_mov_b32_e32 v23, v2
	v_mov_b32_e32 v24, v2
	v_mov_b32_e32 v25, v2
	s_waitcnt vmcnt(0)
	v_mov_b32_e32 v34, v2
	v_mov_b32_e32 v35, v2
	v_mov_b32_e32 v36, v2
	v_mov_b32_e32 v37, v2
	v_mov_b32_e32 v38, v2
	v_mov_b32_e32 v39, v2
	v_mov_b32_e32 v40, v2
	v_mov_b32_e32 v41, v2
	v_mov_b32_e32 v10, v2
	v_mov_b32_e32 v11, v2
	v_mov_b32_e32 v12, v2
	v_mov_b32_e32 v13, v2
	v_mov_b32_e32 v14, v2
	v_mov_b32_e32 v15, v2
	v_mov_b32_e32 v16, v2
	v_mov_b32_e32 v17, v2
	v_mov_b32_e32 v26, v2
	v_mov_b32_e32 v27, v2
	v_mov_b32_e32 v28, v2
	v_mov_b32_e32 v29, v2
	v_mov_b32_e32 v30, v2
	v_mov_b32_e32 v31, v2
	v_mov_b32_e32 v32, v2
	v_mov_b32_e32 v33, v2
	v_mov_b32_e32 v42, v2
	v_mov_b32_e32 v43, v2
	v_mov_b32_e32 v44, v2
	v_mov_b32_e32 v45, v2
	v_mov_b32_e32 v46, v2
	v_mov_b32_e32 v47, v2
	v_mov_b32_e32 v48, v2
	v_mov_b32_e32 v49, v2
	v_mov_b32_e32 v50, v2
	v_mov_b32_e32 v51, v2
	v_mov_b32_e32 v52, v2
	v_mov_b32_e32 v53, v2
	v_mov_b32_e32 v54, v2
	v_mov_b32_e32 v55, v2
	v_mov_b32_e32 v56, v2
	v_mov_b32_e32 v57, v2
	v_mov_b32_e32 v66, v2
	v_mov_b32_e32 v67, v2
	v_mov_b32_e32 v68, v2
	v_mov_b32_e32 v69, v2
	v_mov_b32_e32 v70, v2
	v_mov_b32_e32 v71, v2
	v_mov_b32_e32 v72, v2
	v_mov_b32_e32 v73, v2
	v_mov_b32_e32 v82, v2
	v_mov_b32_e32 v83, v2
	v_mov_b32_e32 v84, v2
	v_mov_b32_e32 v85, v2
	v_mov_b32_e32 v86, v2
	v_mov_b32_e32 v87, v2
	v_mov_b32_e32 v88, v2
	v_mov_b32_e32 v89, v2
	v_mov_b32_e32 v58, v2
	v_mov_b32_e32 v59, v2
	v_mov_b32_e32 v60, v2
	v_mov_b32_e32 v61, v2
	v_mov_b32_e32 v62, v2
	v_mov_b32_e32 v63, v2
	v_mov_b32_e32 v64, v2
	v_mov_b32_e32 v65, v2
	v_mov_b32_e32 v74, v2
	v_mov_b32_e32 v75, v2
	v_mov_b32_e32 v76, v2
	v_mov_b32_e32 v77, v2
	v_mov_b32_e32 v78, v2
	v_mov_b32_e32 v79, v2
	v_mov_b32_e32 v80, v2
	v_mov_b32_e32 v81, v2
	v_mov_b32_e32 v106, v2
	v_mov_b32_e32 v107, v2
	v_mov_b32_e32 v108, v2
	v_mov_b32_e32 v109, v2
	v_mov_b32_e32 v110, v2
	v_mov_b32_e32 v111, v2
	v_mov_b32_e32 v112, v2
	v_mov_b32_e32 v113, v2
	.p2align 6

;     __device__ __forceinline__ size_t aoff(const Unit& u) const { return (size_t)u.pm * bm * lda * 2; }
;     __device__ __forceinline__ size_t boff(const Unit& u) const { return (size_t)u.pn * BM * ldb * 2; }
;     __device__ __forceinline__ size_t aoff(const Unit& u) const { return ((size_t)u.pm * BM * lda + (size_t)u.pn * akoff) * 2; }
;     __device__ __forceinline__ size_t boff(const Unit& u) const { return (size_t)u.pn * BM * ldb * 2; }
;     __device__ __forceinline__ size_t aoff(const Unit& u) const { return ((size_t)u.pm * BM * lda + (size_t)(u.pn >> 1) * akoff) * 2; }
;     __device__ __forceinline__ size_t boff(const Unit& u) const { return (size_t)u.pn * BM * ldb * 2; }
;     ...
;         const bool has_next = S.next(ui + 1, nxt);
;         const char* nA = has_next ? (const char*)g.A + S.aoff(nxt) : cA; const char* nB = has_next ? (const char*)g.Bt + S.boff(nxt) : cB;
;         if constexpr (Epi::PRE) E.pre(lds, cur, wid);
;         for (int t = 0; t < nt; t += 2) {
;             const bool last = (t == nt - 2);
;             const char* a1 = cA + (size_t)(t + 1) * kstep;
;             const char* a2 = last ? nA : cA + (size_t)(t + 2) * kstep; const char* b2 = last ? nB : cB + (size_t)(t + 2) * kstep;
;             const char* a3 = a2 + kstep; const char* b3 = b2 + kstep;
;     ...
; #pragma unroll
;         for (int a = 0; a < 2; ++a)
; #pragma unroll
;             for (int b = 0; b < 2; ++b)
; #pragma unroll
;                 for (int m = 0; m < NM; ++m)
; #pragma unroll
;                     for (int n = 0; n < 2; ++n) acc[a][b][m][n] = (f32x4){0.f, 0.f, 0.f, 0.f};
;         cur = nxt; cA = nA; cB = nB; ++ui; cur.par = ui & 1;
.LBB0_1782:
	s_ashr_i32 s41, s40, 31
	s_lshl_b64 s[2:3], s[40:41], 20
	s_add_u32 s42, s33, s2
	s_addc_u32 s43, s48, s3
	s_and_b64 s[2:3], s[6:7], exec
	s_cselect_b32 s2, s43, s13
	s_cselect_b32 s3, s42, s12
	s_ashr_i32 s37, s36, 31
	s_lshl_b64 s[44:45], s[36:37], 20
	s_add_u32 s44, s60, s44
	s_addc_u32 s45, s63, s45
	s_and_b64 s[46:47], s[6:7], exec
	s_cselect_b32 s9, s45, s15
	s_cselect_b32 s11, s44, s14
	s_add_u32 s12, s12, 0x80080
	s_addc_u32 s13, s13, 0
	s_add_u32 s37, s14, 0x100
	v_mov_b32_e32 v50, 0
	s_addc_u32 s41, s15, 0
	s_mov_b32 vcc_lo, -2
	v_mov_b32_e32 v51, v50
	v_mov_b32_e32 v52, v50
	v_mov_b32_e32 v53, v50
	s_waitcnt vmcnt(0)
	v_mov_b32_e32 v74, v50
	v_mov_b32_e32 v75, v50
	v_mov_b32_e32 v76, v50
	v_mov_b32_e32 v77, v50
	v_mov_b32_e32 v2, v50
	v_mov_b32_e32 v3, v50
	v_mov_b32_e32 v4, v50
	v_mov_b32_e32 v5, v50
	v_mov_b32_e32 v26, v50
	v_mov_b32_e32 v27, v50
	v_mov_b32_e32 v28, v50
	v_mov_b32_e32 v29, v50
	v_mov_b32_e32 v6, v50
	v_mov_b32_e32 v7, v50
	v_mov_b32_e32 v8, v50
	v_mov_b32_e32 v9, v50
	v_mov_b32_e32 v30, v50
	v_mov_b32_e32 v31, v50
	v_mov_b32_e32 v32, v50
	v_mov_b32_e32 v33, v50
	v_mov_b32_e32 v10, v50
	v_mov_b32_e32 v11, v50
	v_mov_b32_e32 v12, v50
	v_mov_b32_e32 v13, v50
	v_mov_b32_e32 v34, v50
	v_mov_b32_e32 v35, v50
	v_mov_b32_e32 v36, v50
	v_mov_b32_e32 v37, v50
	v_mov_b32_e32 v54, v50
	v_mov_b32_e32 v55, v50
	v_mov_b32_e32 v56, v50
	v_mov_b32_e32 v57, v50
	v_mov_b32_e32 v78, v50
	v_mov_b32_e32 v79, v50
	v_mov_b32_e32 v80, v50
	v_mov_b32_e32 v81, v50
	v_mov_b32_e32 v14, v50
	v_mov_b32_e32 v15, v50
	v_mov_b32_e32 v16, v50
	v_mov_b32_e32 v17, v50
	v_mov_b32_e32 v38, v50
	v_mov_b32_e32 v39, v50
	v_mov_b32_e32 v40, v50
	v_mov_b32_e32 v41, v50
	v_mov_b32_e32 v18, v50
	v_mov_b32_e32 v19, v50
	v_mov_b32_e32 v20, v50
	v_mov_b32_e32 v21, v50
	v_mov_b32_e32 v42, v50
	v_mov_b32_e32 v43, v50
	v_mov_b32_e32 v44, v50
	v_mov_b32_e32 v45, v50
	v_mov_b32_e32 v22, v50
	v_mov_b32_e32 v23, v50
	v_mov_b32_e32 v24, v50
	v_mov_b32_e32 v25, v50
	v_mov_b32_e32 v46, v50
	v_mov_b32_e32 v47, v50
	v_mov_b32_e32 v48, v50
	v_mov_b32_e32 v49, v50
	v_mov_b32_e32 v82, v50
	v_mov_b32_e32 v83, v50
	v_mov_b32_e32 v84, v50
	v_mov_b32_e32 v85, v50
	v_mov_b32_e32 v114, v50
	v_mov_b32_e32 v115, v50
	v_mov_b32_e32 v116, v50
	v_mov_b32_e32 v117, v50
	v_mov_b32_e32 v58, v50
	v_mov_b32_e32 v59, v50
	v_mov_b32_e32 v60, v50
	v_mov_b32_e32 v61, v50
	v_mov_b32_e32 v98, v50
	v_mov_b32_e32 v99, v50
	v_mov_b32_e32 v100, v50
	v_mov_b32_e32 v101, v50
	v_mov_b32_e32 v62, v50
	v_mov_b32_e32 v63, v50
	v_mov_b32_e32 v64, v50
	v_mov_b32_e32 v65, v50
	v_mov_b32_e32 v102, v50
	v_mov_b32_e32 v103, v50
	v_mov_b32_e32 v104, v50
	v_mov_b32_e32 v105, v50
	v_mov_b32_e32 v90, v50
	v_mov_b32_e32 v91, v50
	v_mov_b32_e32 v92, v50
	v_mov_b32_e32 v93, v50
	v_mov_b32_e32 v122, v50
	v_mov_b32_e32 v123, v50
	v_mov_b32_e32 v124, v50
	v_mov_b32_e32 v125, v50
	v_mov_b32_e32 v86, v50
	v_mov_b32_e32 v87, v50
	v_mov_b32_e32 v88, v50
	v_mov_b32_e32 v89, v50
	v_mov_b32_e32 v118, v50
	v_mov_b32_e32 v119, v50
	v_mov_b32_e32 v120, v50
	v_mov_b32_e32 v121, v50
	v_mov_b32_e32 v66, v50
	v_mov_b32_e32 v67, v50
	v_mov_b32_e32 v68, v50
	v_mov_b32_e32 v69, v50
	v_mov_b32_e32 v106, v50
	v_mov_b32_e32 v107, v50
	v_mov_b32_e32 v108, v50
	v_mov_b32_e32 v109, v50
	v_mov_b32_e32 v70, v50
	v_mov_b32_e32 v71, v50
	v_mov_b32_e32 v72, v50
	v_mov_b32_e32 v73, v50
	v_mov_b32_e32 v110, v50
	v_mov_b32_e32 v111, v50
	v_mov_b32_e32 v112, v50
	v_mov_b32_e32 v113, v50
	v_mov_b32_e32 v94, v50
	v_mov_b32_e32 v95, v50
	v_mov_b32_e32 v96, v50
	v_mov_b32_e32 v97, v50
	v_mov_b32_e32 v126, v50
	v_mov_b32_e32 v127, v50
	v_mov_b32_e32 v128, v50
	v_mov_b32_e32 v129, v50
	.p2align 6

;     ...
;             const char* a1 = cA + (size_t)(t + 1) * kstep;
;             const char* a2 = last ? nA : cA + (size_t)(t + 2) * kstep; const char* b2 = last ? nB : cB + (size_t)(t + 2) * kstep;
;             const char* a3 = a2 + kstep; const char* b3 = b2 + kstep;
;     ...
; #pragma unroll
;         for (int a = 0; a < 2; ++a)
; #pragma unroll
;             for (int b = 0; b < 2; ++b)
; #pragma unroll
;                 for (int m = 0; m < NM; ++m)
; #pragma unroll
;                     for (int n = 0; n < 2; ++n) acc[a][b][m][n] = (f32x4){0.f, 0.f, 0.f, 0.f};
;         cur = nxt; cA = nA; cB = nB; ++ui; cur.par = ui & 1;
.LBB0_2157:
	s_add_u32 s2, s16, 0x100
	v_mov_b32_e32 v2, 0
	s_addc_u32 s3, s17, 0
	s_mov_b32 s60, -2
	v_mov_b32_e32 v3, v2
	v_mov_b32_e32 v4, v2
	v_mov_b32_e32 v5, v2
	v_mov_b32_e32 v6, v2
	v_mov_b32_e32 v7, v2
	v_mov_b32_e32 v8, v2
	v_mov_b32_e32 v9, v2
	v_mov_b32_e32 v18, v2
	v_mov_b32_e32 v19, v2
	v_mov_b32_e32 v20, v2
	v_mov_b32_e32 v21, v2
	v_mov_b32_e32 v22, v2
	v_mov_b32_e32 v23, v2
	v_mov_b32_e32 v24, v2
	v_mov_b32_e32 v25, v2
	s_waitcnt vmcnt(0)
	v_mov_b32_e32 v34, v2
	v_mov_b32_e32 v35, v2
	v_mov_b32_e32 v36, v2
	v_mov_b32_e32 v37, v2
	v_mov_b32_e32 v38, v2
	v_mov_b32_e32 v39, v2
	v_mov_b32_e32 v40, v2
	v_mov_b32_e32 v41, v2
	v_mov_b32_e32 v10, v2
	v_mov_b32_e32 v11, v2
	v_mov_b32_e32 v12, v2
	v_mov_b32_e32 v13, v2
	v_mov_b32_e32 v14, v2
	v_mov_b32_e32 v15, v2
	v_mov_b32_e32 v16, v2
	v_mov_b32_e32 v17, v2
	v_mov_b32_e32 v26, v2
	v_mov_b32_e32 v27, v2
	v_mov_b32_e32 v28, v2
	v_mov_b32_e32 v29, v2
	v_mov_b32_e32 v30, v2
	v_mov_b32_e32 v31, v2
	v_mov_b32_e32 v32, v2
	v_mov_b32_e32 v33, v2
	v_mov_b32_e32 v42, v2
	v_mov_b32_e32 v43, v2
	v_mov_b32_e32 v44, v2
	v_mov_b32_e32 v45, v2
	v_mov_b32_e32 v46, v2
	v_mov_b32_e32 v47, v2
	v_mov_b32_e32 v48, v2
	v_mov_b32_e32 v49, v2
	v_mov_b32_e32 v50, v2
	v_mov_b32_e32 v51, v2
	v_mov_b32_e32 v52, v2
	v_mov_b32_e32 v53, v2
	v_mov_b32_e32 v54, v2
	v_mov_b32_e32 v55, v2
	v_mov_b32_e32 v56, v2
	v_mov_b32_e32 v57, v2
	v_mov_b32_e32 v66, v2
	v_mov_b32_e32 v67, v2
	v_mov_b32_e32 v68, v2
	v_mov_b32_e32 v69, v2
	v_mov_b32_e32 v70, v2
	v_mov_b32_e32 v71, v2
	v_mov_b32_e32 v72, v2
	v_mov_b32_e32 v73, v2
	v_mov_b32_e32 v82, v2
	v_mov_b32_e32 v83, v2
	v_mov_b32_e32 v84, v2
	v_mov_b32_e32 v85, v2
	v_mov_b32_e32 v86, v2
	v_mov_b32_e32 v87, v2
	v_mov_b32_e32 v88, v2
	v_mov_b32_e32 v89, v2
	v_mov_b32_e32 v58, v2
	v_mov_b32_e32 v59, v2
	v_mov_b32_e32 v60, v2
	v_mov_b32_e32 v61, v2
	v_mov_b32_e32 v62, v2
	v_mov_b32_e32 v63, v2
	v_mov_b32_e32 v64, v2
	v_mov_b32_e32 v65, v2
	v_mov_b32_e32 v74, v2
	v_mov_b32_e32 v75, v2
	v_mov_b32_e32 v76, v2
	v_mov_b32_e32 v77, v2
	v_mov_b32_e32 v78, v2
	v_mov_b32_e32 v79, v2
	v_mov_b32_e32 v80, v2
	v_mov_b32_e32 v81, v2
	v_mov_b32_e32 v106, v2
	v_mov_b32_e32 v107, v2
	v_mov_b32_e32 v108, v2
	v_mov_b32_e32 v109, v2
	v_mov_b32_e32 v110, v2
	v_mov_b32_e32 v111, v2
	v_mov_b32_e32 v112, v2
	v_mov_b32_e32 v113, v2
	.p2align 6
